# rw_finish: software-pipelined loop (next iteration loads before current arithmetic, two register sets)
# speedup vs baseline: 1.0120x; 1.0040x over previous
.LBB0_166:
	s_ashr_i32 s4, s40, 3
	s_mov_b32 s7, s73
	s_mov_b32 s6, 0x3a27c5ac
	s_ashr_i32 s5, s4, 31
	v_mov_b64_e32 v[4:5], s[6:7]
	s_mul_hi_i32 s6, s4, 0xc00
	s_mul_i32 s8, s4, 0xc00
	s_lshl_b64 s[4:5], s[4:5], 9
	v_lshl_add_u64 v[36:37], s[4:5], 0, v[2:3]
	s_add_u32 s4, s12, s8
	s_addc_u32 s5, s13, s6
	s_and_b32 s72, s29, 0x100
	s_mov_b32 s9, s73
	s_mov_b32 s37, s73
	s_mov_b32 s39, s73
	s_or_b32 s8, s72, 64
	s_or_b32 s36, s72, 0x80
	s_or_b32 s38, s72, 0xc0
	v_add_u32_e32 v44, s72, v2
	v_lshl_add_u64 v[40:41], v[2:3], 1, s[4:5]
	v_lshl_add_u64 v[42:43], v[36:37], 0, s[72:73]
	s_lshl_b32 s6, s72, 1
	v_lshl_add_u64 v[46:47], v[36:37], 0, s[8:9]
	v_lshl_add_u64 v[48:49], v[36:37], 0, s[36:37]
	v_lshl_add_u64 v[50:51], v[36:37], 0, s[38:39]
	v_ashrrev_i32_e32 v45, 31, v44
	v_lshl_add_u64 v[40:41], v[40:41], 0, s[6:7]
	v_lshlrev_b64 v[42:43], 1, v[42:43]
	s_mov_b64 s[4:5], 0xe8c0800
	v_lshlrev_b64 v[46:47], 1, v[46:47]
	v_lshlrev_b64 v[48:49], 1, v[48:49]
	v_lshlrev_b64 v[50:51], 1, v[50:51]
	v_lshlrev_b64 v[44:45], 2, v[44:45]
	v_lshl_add_u64 v[36:37], v[40:41], 0, s[4:5]
	v_lshl_add_u64 v[52:53], s[14:15], 0, v[42:43]
	v_lshl_add_u64 v[42:43], s[20:21], 0, v[42:43]
	v_add_co_u32_e32 v40, vcc, s81, v40
	v_lshl_add_u64 v[54:55], s[14:15], 0, v[46:47]
	v_lshl_add_u64 v[46:47], s[20:21], 0, v[46:47]
	v_lshl_add_u64 v[56:57], s[14:15], 0, v[48:49]
	v_lshl_add_u64 v[48:49], s[20:21], 0, v[48:49]
	v_lshl_add_u64 v[58:59], s[14:15], 0, v[50:51]
	v_lshl_add_u64 v[50:51], s[20:21], 0, v[50:51]
	v_lshl_add_u64 v[60:61], s[30:31], 0, v[44:45]
	v_addc_co_u32_e32 v41, vcc, 0, v41, vcc
	v_lshl_add_u64 v[44:45], s[34:35], 0, v[44:45]
	global_load_ushort v0, v[52:53], off
	s_nop 0
	global_load_ushort v42, v[42:43], off
	s_nop 0
	global_load_ushort v43, v[36:37], off offset:128
	global_load_ushort v52, v[36:37], off offset:256
	global_load_ushort v53, v[36:37], off offset:384
	s_nop 0
	global_load_ushort v54, v[54:55], off
	s_nop 0
	global_load_ushort v46, v[46:47], off
	s_nop 0
	global_load_ushort v47, v[40:41], off offset:2048
	global_load_ushort v55, v[56:57], off
	s_nop 0
	global_load_ushort v48, v[48:49], off
	s_nop 0
	global_load_ushort v49, v[58:59], off
	s_nop 0
	global_load_ushort v50, v[50:51], off
	s_nop 0
	global_load_dword v51, v[60:61], off
	global_load_dword v56, v[60:61], off offset:256
	global_load_dword v57, v[60:61], off offset:512
	global_load_dword v58, v[60:61], off offset:768
	global_load_dword v59, v[44:45], off
	s_nop 0
	global_load_dword v60, v[44:45], off offset:256
	global_load_dword v61, v[44:45], off offset:512
	global_load_dword v62, v[44:45], off offset:768
	s_add_i32 s40, s40, s41
	s_add_i32 s29, s29, s80
	s_cmp_lt_i32 s40, 0x21000
	s_cselect_b32 s98, 1, 0
	global_load_ushort v128, v[36:37], off offset:128
	global_load_ushort v128, v[36:37], off offset:128
	global_load_ushort v128, v[36:37], off offset:128
	global_load_ushort v128, v[36:37], off offset:128
.Lrwf_loop:
	s_cmp_eq_u32 s98, 0
	s_cbranch_scc1 .Lrwf_tail1
	s_ashr_i32 s4, s40, 3
	s_mov_b32 s7, s73
	s_mov_b32 s6, 0x3a27c5ac
	s_ashr_i32 s5, s4, 31
	v_mov_b64_e32 v[68:69], s[6:7]
	s_mul_hi_i32 s6, s4, 0xc00
	s_mul_i32 s8, s4, 0xc00
	s_lshl_b64 s[4:5], s[4:5], 9
	v_lshl_add_u64 v[100:101], s[4:5], 0, v[2:3]
	s_add_u32 s4, s12, s8
	s_addc_u32 s5, s13, s6
	s_and_b32 s72, s29, 0x100
	s_mov_b32 s9, s73
	s_mov_b32 s37, s73
	s_mov_b32 s39, s73
	s_or_b32 s8, s72, 64
	s_or_b32 s36, s72, 0x80
	s_or_b32 s38, s72, 0xc0
	v_add_u32_e32 v108, s72, v2
	v_lshl_add_u64 v[104:105], v[2:3], 1, s[4:5]
	v_lshl_add_u64 v[106:107], v[100:101], 0, s[72:73]
	s_lshl_b32 s6, s72, 1
	v_lshl_add_u64 v[110:111], v[100:101], 0, s[8:9]
	v_lshl_add_u64 v[112:113], v[100:101], 0, s[36:37]
	v_lshl_add_u64 v[114:115], v[100:101], 0, s[38:39]
	v_ashrrev_i32_e32 v109, 31, v108
	v_lshl_add_u64 v[104:105], v[104:105], 0, s[6:7]
	v_lshlrev_b64 v[106:107], 1, v[106:107]
	s_mov_b64 s[4:5], 0xe8c0800
	v_lshlrev_b64 v[110:111], 1, v[110:111]
	v_lshlrev_b64 v[112:113], 1, v[112:113]
	v_lshlrev_b64 v[114:115], 1, v[114:115]
	v_lshlrev_b64 v[108:109], 2, v[108:109]
	v_lshl_add_u64 v[100:101], v[104:105], 0, s[4:5]
	v_lshl_add_u64 v[116:117], s[14:15], 0, v[106:107]
	v_lshl_add_u64 v[106:107], s[20:21], 0, v[106:107]
	v_add_co_u32_e32 v104, vcc, s81, v104
	v_lshl_add_u64 v[118:119], s[14:15], 0, v[110:111]
	v_lshl_add_u64 v[110:111], s[20:21], 0, v[110:111]
	v_lshl_add_u64 v[120:121], s[14:15], 0, v[112:113]
	v_lshl_add_u64 v[112:113], s[20:21], 0, v[112:113]
	v_lshl_add_u64 v[122:123], s[14:15], 0, v[114:115]
	v_lshl_add_u64 v[114:115], s[20:21], 0, v[114:115]
	v_lshl_add_u64 v[124:125], s[30:31], 0, v[108:109]
	v_addc_co_u32_e32 v105, vcc, 0, v105, vcc
	v_lshl_add_u64 v[108:109], s[34:35], 0, v[108:109]
	global_load_ushort v64, v[116:117], off
	s_nop 0
	global_load_ushort v106, v[106:107], off
	s_nop 0
	global_load_ushort v107, v[100:101], off offset:128
	global_load_ushort v116, v[100:101], off offset:256
	global_load_ushort v117, v[100:101], off offset:384
	s_nop 0
	global_load_ushort v118, v[118:119], off
	s_nop 0
	global_load_ushort v110, v[110:111], off
	s_nop 0
	global_load_ushort v111, v[104:105], off offset:2048
	global_load_ushort v119, v[120:121], off
	s_nop 0
	global_load_ushort v112, v[112:113], off
	s_nop 0
	global_load_ushort v113, v[122:123], off
	s_nop 0
	global_load_ushort v114, v[114:115], off
	s_nop 0
	global_load_dword v115, v[124:125], off
	global_load_dword v120, v[124:125], off offset:256
	global_load_dword v121, v[124:125], off offset:512
	global_load_dword v122, v[124:125], off offset:768
	global_load_dword v123, v[108:109], off
	s_nop 0
	global_load_dword v124, v[108:109], off offset:256
	global_load_dword v125, v[108:109], off offset:512
	global_load_dword v126, v[108:109], off offset:768
	s_add_i32 s40, s40, s41
	s_add_i32 s29, s29, s80
	s_cmp_lt_i32 s40, 0x21000
	s_cselect_b32 s98, 1, 0
	v_mov_b32_e32 v35, v1
	v_mov_b32_e32 v34, v1
	v_mov_b32_e32 v15, v1
	v_mov_b32_e32 v14, v1
	v_mov_b32_e32 v39, v1
	v_mov_b32_e32 v38, v1
	v_mov_b32_e32 v21, v1
	v_mov_b32_e32 v20, v1
	v_mov_b32_e32 v33, v1
	v_mov_b32_e32 v32, v1
	v_mov_b32_e32 v19, v1
	v_mov_b32_e32 v18, v1
	v_mov_b32_e32 v31, v1
	v_mov_b32_e32 v30, v1
	v_mov_b32_e32 v17, v1
	v_mov_b32_e32 v16, v1
	v_mov_b32_e32 v29, v1
	v_mov_b32_e32 v28, v1
	v_mov_b32_e32 v13, v1
	v_mov_b32_e32 v12, v1
	v_mov_b32_e32 v27, v1
	v_mov_b32_e32 v26, v1
	v_mov_b32_e32 v11, v1
	v_mov_b32_e32 v10, v1
	v_mov_b32_e32 v25, v1
	v_mov_b32_e32 v24, v1
	v_mov_b32_e32 v9, v1
	v_mov_b32_e32 v8, v1
	v_mov_b32_e32 v23, v1
	v_mov_b32_e32 v22, v1
	v_mov_b32_e32 v7, v1
	v_mov_b32_e32 v6, v1
	s_waitcnt vmcnt(43)
	v_lshlrev_b32_e32 v0, 16, v0
	s_waitcnt vmcnt(42)
	v_lshlrev_b32_e32 v63, 16, v42
	s_waitcnt vmcnt(41)
	v_lshlrev_b32_e32 v42, 16, v43
	s_waitcnt vmcnt(40)
	v_lshlrev_b32_e32 v45, 16, v52
	s_waitcnt vmcnt(39)
	v_lshlrev_b32_e32 v44, 16, v53
	v_mov_b32_dpp v14, v42 quad_perm:[1,0,3,2] row_mask:0xf bank_mask:0xf
	v_mov_b32_dpp v35, v45 quad_perm:[1,0,3,2] row_mask:0xf bank_mask:0xf
	s_waitcnt vmcnt(36)
	v_lshlrev_b32_e32 v43, 16, v47
	v_mov_b32_dpp v34, v44 quad_perm:[1,0,3,2] row_mask:0xf bank_mask:0xf
	v_pk_add_f32 v[34:35], v[44:45], v[34:35]
	v_mov_b32_dpp v15, v43 quad_perm:[1,0,3,2] row_mask:0xf bank_mask:0xf
	v_pk_add_f32 v[14:15], v[42:43], v[14:15]
	v_mov_b32_dpp v39, v35 quad_perm:[2,3,0,1] row_mask:0xf bank_mask:0xf
	v_mov_b32_dpp v38, v34 quad_perm:[2,3,0,1] row_mask:0xf bank_mask:0xf
	v_mov_b32_dpp v21, v15 quad_perm:[2,3,0,1] row_mask:0xf bank_mask:0xf
	v_mov_b32_dpp v20, v14 quad_perm:[2,3,0,1] row_mask:0xf bank_mask:0xf
	v_pk_add_f32 v[34:35], v[34:35], v[38:39]
	v_pk_add_f32 v[14:15], v[14:15], v[20:21]
	s_waitcnt vmcnt(35)
	v_lshlrev_b32_e32 v52, 16, v55
	v_mov_b32_dpp v33, v35 row_half_mirror row_mask:0xf bank_mask:0xf
	v_mov_b32_dpp v32, v34 row_half_mirror row_mask:0xf bank_mask:0xf
	v_mov_b32_dpp v19, v15 row_half_mirror row_mask:0xf bank_mask:0xf
	v_mov_b32_dpp v18, v14 row_half_mirror row_mask:0xf bank_mask:0xf
	v_pk_add_f32 v[20:21], v[34:35], v[32:33]
	v_pk_add_f32 v[14:15], v[14:15], v[18:19]
	v_lshlrev_b32_e32 v47, 16, v54
	v_mov_b32_dpp v31, v21 row_mirror row_mask:0xf bank_mask:0xf
	v_mov_b32_dpp v30, v20 row_mirror row_mask:0xf bank_mask:0xf
	v_mov_b32_dpp v17, v15 row_mirror row_mask:0xf bank_mask:0xf
	v_mov_b32_dpp v16, v14 row_mirror row_mask:0xf bank_mask:0xf
	v_pk_add_f32 v[18:19], v[20:21], v[30:31]
	v_pk_add_f32 v[14:15], v[14:15], v[16:17]
	ds_bpermute_b32 v17, v167, v19
	ds_bpermute_b32 v16, v167, v18
	ds_bpermute_b32 v21, v167, v15
	ds_bpermute_b32 v20, v167, v14
	s_waitcnt vmcnt(34)
	v_lshlrev_b32_e32 v48, 16, v48
	s_waitcnt vmcnt(33)
	v_lshlrev_b32_e32 v49, 16, v49
	s_waitcnt lgkmcnt(2)
	v_pk_add_f32 v[16:17], v[18:19], v[16:17]
	ds_bpermute_b32 v19, v168, v17
	s_waitcnt lgkmcnt(1)
	v_pk_add_f32 v[14:15], v[14:15], v[20:21]
	ds_bpermute_b32 v18, v168, v16
	ds_bpermute_b32 v21, v168, v15
	ds_bpermute_b32 v20, v168, v14
	v_lshlrev_b32_e32 v46, 16, v46
	s_waitcnt vmcnt(32)
	v_lshlrev_b32_e32 v50, 16, v50
	s_waitcnt lgkmcnt(2)
	v_pk_add_f32 v[16:17], v[16:17], v[18:19]
	s_waitcnt lgkmcnt(0)
	v_pk_add_f32 v[14:15], v[14:15], v[20:21]
	v_pk_fma_f32 v[16:17], v[16:17], s[42:43], v[44:45] op_sel_hi:[1,0,1] neg_lo:[1,0,0] neg_hi:[1,0,0]
	v_pk_fma_f32 v[14:15], v[14:15], s[42:43], v[42:43] op_sel_hi:[1,0,1] neg_lo:[1,0,0] neg_hi:[1,0,0]
	v_pk_mul_f32 v[18:19], v[16:17], v[16:17]
	v_pk_mul_f32 v[20:21], v[14:15], v[14:15]
	s_nop 0
	v_mov_b32_dpp v29, v19 quad_perm:[1,0,3,2] row_mask:0xf bank_mask:0xf
	v_mov_b32_dpp v28, v18 quad_perm:[1,0,3,2] row_mask:0xf bank_mask:0xf
	v_mov_b32_dpp v13, v21 quad_perm:[1,0,3,2] row_mask:0xf bank_mask:0xf
	v_mov_b32_dpp v12, v20 quad_perm:[1,0,3,2] row_mask:0xf bank_mask:0xf
	v_pk_fma_f32 v[18:19], v[16:17], v[16:17], v[28:29]
	v_pk_fma_f32 v[12:13], v[14:15], v[14:15], v[12:13]
	s_nop 0
	v_mov_b32_dpp v27, v19 quad_perm:[2,3,0,1] row_mask:0xf bank_mask:0xf
	v_mov_b32_dpp v26, v18 quad_perm:[2,3,0,1] row_mask:0xf bank_mask:0xf
	v_mov_b32_dpp v11, v13 quad_perm:[2,3,0,1] row_mask:0xf bank_mask:0xf
	v_mov_b32_dpp v10, v12 quad_perm:[2,3,0,1] row_mask:0xf bank_mask:0xf
	v_pk_add_f32 v[18:19], v[18:19], v[26:27]
	v_pk_add_f32 v[10:11], v[12:13], v[10:11]
	s_nop 0
	v_mov_b32_dpp v25, v19 row_half_mirror row_mask:0xf bank_mask:0xf
	v_mov_b32_dpp v24, v18 row_half_mirror row_mask:0xf bank_mask:0xf
	v_mov_b32_dpp v9, v11 row_half_mirror row_mask:0xf bank_mask:0xf
	v_mov_b32_dpp v8, v10 row_half_mirror row_mask:0xf bank_mask:0xf
	v_pk_add_f32 v[12:13], v[18:19], v[24:25]
	v_pk_add_f32 v[8:9], v[10:11], v[8:9]
	s_nop 0
	v_mov_b32_dpp v23, v13 row_mirror row_mask:0xf bank_mask:0xf
	v_mov_b32_dpp v22, v12 row_mirror row_mask:0xf bank_mask:0xf
	v_mov_b32_dpp v7, v9 row_mirror row_mask:0xf bank_mask:0xf
	v_mov_b32_dpp v6, v8 row_mirror row_mask:0xf bank_mask:0xf
	v_pk_add_f32 v[10:11], v[12:13], v[22:23]
	v_pk_add_f32 v[6:7], v[8:9], v[6:7]
	ds_bpermute_b32 v9, v167, v11
	ds_bpermute_b32 v8, v167, v10
	ds_bpermute_b32 v13, v167, v7
	ds_bpermute_b32 v12, v167, v6
	s_waitcnt lgkmcnt(2)
	v_pk_add_f32 v[8:9], v[10:11], v[8:9]
	ds_bpermute_b32 v11, v168, v9
	s_waitcnt lgkmcnt(1)
	v_pk_add_f32 v[6:7], v[6:7], v[12:13]
	ds_bpermute_b32 v10, v168, v8
	ds_bpermute_b32 v13, v168, v7
	ds_bpermute_b32 v12, v168, v6
	s_waitcnt lgkmcnt(2)
	v_pk_add_f32 v[8:9], v[8:9], v[10:11]
	s_nop 0
	v_pk_fma_f32 v[8:9], v[8:9], s[42:43], v[4:5] op_sel_hi:[1,0,0]
	s_waitcnt lgkmcnt(0)
	v_pk_add_f32 v[6:7], v[6:7], v[12:13]
	v_cmp_gt_f32_e64 s[4:5], s74, v9
	v_pk_fma_f32 v[4:5], v[6:7], s[42:43], v[4:5] op_sel_hi:[1,0,0]
	v_mul_f32_e32 v6, 0x4b800000, v9
	v_mul_f32_e32 v7, 0x4b800000, v8
	v_cmp_gt_f32_e32 vcc, s74, v8
	v_mul_f32_e32 v10, 0x4b800000, v5
	v_mul_f32_e32 v11, 0x4b800000, v4
	v_cmp_gt_f32_e64 s[6:7], s74, v4
	v_cndmask_b32_e64 v6, v9, v6, s[4:5]
	v_cmp_gt_f32_e64 s[8:9], s74, v5
	v_cndmask_b32_e32 v7, v8, v7, vcc
	v_cndmask_b32_e64 v4, v4, v11, s[6:7]
	v_cndmask_b32_e64 v5, v5, v10, s[8:9]
	v_rsq_f32_e32 v6, v6
	v_rsq_f32_e32 v7, v7
	v_rsq_f32_e32 v5, v5
	v_rsq_f32_e32 v4, v4
	v_mul_f32_e32 v8, 0x45800000, v6
	v_mul_f32_e32 v9, 0x45800000, v7
	v_mul_f32_e32 v10, 0x45800000, v5
	v_mul_f32_e32 v11, 0x45800000, v4
	v_cndmask_b32_e64 v6, v6, v8, s[4:5]
	v_cndmask_b32_e32 v7, v7, v9, vcc
	v_cndmask_b32_e64 v5, v5, v10, s[8:9]
	v_cndmask_b32_e64 v4, v4, v11, s[6:7]
	v_mul_f32_e32 v6, v17, v6
	v_mul_f32_e32 v7, v16, v7
	v_mul_f32_e32 v5, v15, v5
	v_mul_f32_e32 v4, v14, v4
	s_waitcnt vmcnt(25)
	v_fmac_f32_e32 v61, v57, v6
	s_waitcnt vmcnt(24)
	v_fmac_f32_e32 v62, v58, v7
	v_fmac_f32_e32 v59, v51, v5
	v_fmac_f32_e32 v60, v56, v4
	v_add_f32_e32 v4, v61, v52
	v_add_f32_e32 v5, v62, v49
	v_add_f32_e32 v0, v59, v0
	v_add_f32_e32 v6, v60, v47
	v_mul_f32_e32 v4, v4, v48
	v_mul_f32_e32 v5, v5, v50
	v_mul_f32_e32 v0, v0, v63
	v_mul_f32_e32 v6, v6, v46
	v_bfe_u32 v7, v4, 16, 1
	v_bfe_u32 v8, v5, 16, 1
	v_bfe_u32 v9, v0, 16, 1
	v_bfe_u32 v10, v6, 16, 1
	v_add3_u32 v4, v4, v7, s78
	v_add3_u32 v5, v5, v8, s78
	v_add3_u32 v0, v0, v9, s78
	v_add3_u32 v6, v6, v10, s78
	global_store_short_d16_hi v[36:37], v4, off offset:256
	global_store_short_d16_hi v[36:37], v5, off offset:384
	global_store_short_d16_hi v[40:41], v0, off offset:2048
	global_store_short_d16_hi v[36:37], v6, off offset:128
	s_cmp_eq_u32 s98, 0
	s_cbranch_scc1 .Lrwf_tail2
	s_ashr_i32 s4, s40, 3
	s_mov_b32 s7, s73
	s_mov_b32 s6, 0x3a27c5ac
	s_ashr_i32 s5, s4, 31
	v_mov_b64_e32 v[4:5], s[6:7]
	s_mul_hi_i32 s6, s4, 0xc00
	s_mul_i32 s8, s4, 0xc00
	s_lshl_b64 s[4:5], s[4:5], 9
	v_lshl_add_u64 v[36:37], s[4:5], 0, v[2:3]
	s_add_u32 s4, s12, s8
	s_addc_u32 s5, s13, s6
	s_and_b32 s72, s29, 0x100
	s_mov_b32 s9, s73
	s_mov_b32 s37, s73
	s_mov_b32 s39, s73
	s_or_b32 s8, s72, 64
	s_or_b32 s36, s72, 0x80
	s_or_b32 s38, s72, 0xc0
	v_add_u32_e32 v44, s72, v2
	v_lshl_add_u64 v[40:41], v[2:3], 1, s[4:5]
	v_lshl_add_u64 v[42:43], v[36:37], 0, s[72:73]
	s_lshl_b32 s6, s72, 1
	v_lshl_add_u64 v[46:47], v[36:37], 0, s[8:9]
	v_lshl_add_u64 v[48:49], v[36:37], 0, s[36:37]
	v_lshl_add_u64 v[50:51], v[36:37], 0, s[38:39]
	v_ashrrev_i32_e32 v45, 31, v44
	v_lshl_add_u64 v[40:41], v[40:41], 0, s[6:7]
	v_lshlrev_b64 v[42:43], 1, v[42:43]
	s_mov_b64 s[4:5], 0xe8c0800
	v_lshlrev_b64 v[46:47], 1, v[46:47]
	v_lshlrev_b64 v[48:49], 1, v[48:49]
	v_lshlrev_b64 v[50:51], 1, v[50:51]
	v_lshlrev_b64 v[44:45], 2, v[44:45]
	v_lshl_add_u64 v[36:37], v[40:41], 0, s[4:5]
	v_lshl_add_u64 v[52:53], s[14:15], 0, v[42:43]
	v_lshl_add_u64 v[42:43], s[20:21], 0, v[42:43]
	v_add_co_u32_e32 v40, vcc, s81, v40
	v_lshl_add_u64 v[54:55], s[14:15], 0, v[46:47]
	v_lshl_add_u64 v[46:47], s[20:21], 0, v[46:47]
	v_lshl_add_u64 v[56:57], s[14:15], 0, v[48:49]
	v_lshl_add_u64 v[48:49], s[20:21], 0, v[48:49]
	v_lshl_add_u64 v[58:59], s[14:15], 0, v[50:51]
	v_lshl_add_u64 v[50:51], s[20:21], 0, v[50:51]
	v_lshl_add_u64 v[60:61], s[30:31], 0, v[44:45]
	v_addc_co_u32_e32 v41, vcc, 0, v41, vcc
	v_lshl_add_u64 v[44:45], s[34:35], 0, v[44:45]
	global_load_ushort v0, v[52:53], off
	s_nop 0
	global_load_ushort v42, v[42:43], off
	s_nop 0
	global_load_ushort v43, v[36:37], off offset:128
	global_load_ushort v52, v[36:37], off offset:256
	global_load_ushort v53, v[36:37], off offset:384
	s_nop 0
	global_load_ushort v54, v[54:55], off
	s_nop 0
	global_load_ushort v46, v[46:47], off
	s_nop 0
	global_load_ushort v47, v[40:41], off offset:2048
	global_load_ushort v55, v[56:57], off
	s_nop 0
	global_load_ushort v48, v[48:49], off
	s_nop 0
	global_load_ushort v49, v[58:59], off
	s_nop 0
	global_load_ushort v50, v[50:51], off
	s_nop 0
	global_load_dword v51, v[60:61], off
	global_load_dword v56, v[60:61], off offset:256
	global_load_dword v57, v[60:61], off offset:512
	global_load_dword v58, v[60:61], off offset:768
	global_load_dword v59, v[44:45], off
	s_nop 0
	global_load_dword v60, v[44:45], off offset:256
	global_load_dword v61, v[44:45], off offset:512
	global_load_dword v62, v[44:45], off offset:768
	s_add_i32 s40, s40, s41
	s_add_i32 s29, s29, s80
	s_cmp_lt_i32 s40, 0x21000
	s_cselect_b32 s98, 1, 0
	v_mov_b32_e32 v99, v1
	v_mov_b32_e32 v98, v1
	v_mov_b32_e32 v79, v1
	v_mov_b32_e32 v78, v1
	v_mov_b32_e32 v103, v1
	v_mov_b32_e32 v102, v1
	v_mov_b32_e32 v85, v1
	v_mov_b32_e32 v84, v1
	v_mov_b32_e32 v97, v1
	v_mov_b32_e32 v96, v1
	v_mov_b32_e32 v83, v1
	v_mov_b32_e32 v82, v1
	v_mov_b32_e32 v95, v1
	v_mov_b32_e32 v94, v1
	v_mov_b32_e32 v81, v1
	v_mov_b32_e32 v80, v1
	v_mov_b32_e32 v93, v1
	v_mov_b32_e32 v92, v1
	v_mov_b32_e32 v77, v1
	v_mov_b32_e32 v76, v1
	v_mov_b32_e32 v91, v1
	v_mov_b32_e32 v90, v1
	v_mov_b32_e32 v75, v1
	v_mov_b32_e32 v74, v1
	v_mov_b32_e32 v89, v1
	v_mov_b32_e32 v88, v1
	v_mov_b32_e32 v73, v1
	v_mov_b32_e32 v72, v1
	v_mov_b32_e32 v87, v1
	v_mov_b32_e32 v86, v1
	v_mov_b32_e32 v71, v1
	v_mov_b32_e32 v70, v1
	s_waitcnt vmcnt(43)
	v_lshlrev_b32_e32 v64, 16, v64
	s_waitcnt vmcnt(42)
	v_lshlrev_b32_e32 v127, 16, v106
	s_waitcnt vmcnt(41)
	v_lshlrev_b32_e32 v106, 16, v107
	s_waitcnt vmcnt(40)
	v_lshlrev_b32_e32 v109, 16, v116
	s_waitcnt vmcnt(39)
	v_lshlrev_b32_e32 v108, 16, v117
	v_mov_b32_dpp v78, v106 quad_perm:[1,0,3,2] row_mask:0xf bank_mask:0xf
	v_mov_b32_dpp v99, v109 quad_perm:[1,0,3,2] row_mask:0xf bank_mask:0xf
	s_waitcnt vmcnt(36)
	v_lshlrev_b32_e32 v107, 16, v111
	v_mov_b32_dpp v98, v108 quad_perm:[1,0,3,2] row_mask:0xf bank_mask:0xf
	v_pk_add_f32 v[98:99], v[108:109], v[98:99]
	v_mov_b32_dpp v79, v107 quad_perm:[1,0,3,2] row_mask:0xf bank_mask:0xf
	v_pk_add_f32 v[78:79], v[106:107], v[78:79]
	v_mov_b32_dpp v103, v99 quad_perm:[2,3,0,1] row_mask:0xf bank_mask:0xf
	v_mov_b32_dpp v102, v98 quad_perm:[2,3,0,1] row_mask:0xf bank_mask:0xf
	v_mov_b32_dpp v85, v79 quad_perm:[2,3,0,1] row_mask:0xf bank_mask:0xf
	v_mov_b32_dpp v84, v78 quad_perm:[2,3,0,1] row_mask:0xf bank_mask:0xf
	v_pk_add_f32 v[98:99], v[98:99], v[102:103]
	v_pk_add_f32 v[78:79], v[78:79], v[84:85]
	s_waitcnt vmcnt(35)
	v_lshlrev_b32_e32 v116, 16, v119
	v_mov_b32_dpp v97, v99 row_half_mirror row_mask:0xf bank_mask:0xf
	v_mov_b32_dpp v96, v98 row_half_mirror row_mask:0xf bank_mask:0xf
	v_mov_b32_dpp v83, v79 row_half_mirror row_mask:0xf bank_mask:0xf
	v_mov_b32_dpp v82, v78 row_half_mirror row_mask:0xf bank_mask:0xf
	v_pk_add_f32 v[84:85], v[98:99], v[96:97]
	v_pk_add_f32 v[78:79], v[78:79], v[82:83]
	v_lshlrev_b32_e32 v111, 16, v118
	v_mov_b32_dpp v95, v85 row_mirror row_mask:0xf bank_mask:0xf
	v_mov_b32_dpp v94, v84 row_mirror row_mask:0xf bank_mask:0xf
	v_mov_b32_dpp v81, v79 row_mirror row_mask:0xf bank_mask:0xf
	v_mov_b32_dpp v80, v78 row_mirror row_mask:0xf bank_mask:0xf
	v_pk_add_f32 v[82:83], v[84:85], v[94:95]
	v_pk_add_f32 v[78:79], v[78:79], v[80:81]
	ds_bpermute_b32 v81, v167, v83
	ds_bpermute_b32 v80, v167, v82
	ds_bpermute_b32 v85, v167, v79
	ds_bpermute_b32 v84, v167, v78
	s_waitcnt vmcnt(34)
	v_lshlrev_b32_e32 v112, 16, v112
	s_waitcnt vmcnt(33)
	v_lshlrev_b32_e32 v113, 16, v113
	s_waitcnt lgkmcnt(2)
	v_pk_add_f32 v[80:81], v[82:83], v[80:81]
	ds_bpermute_b32 v83, v168, v81
	s_waitcnt lgkmcnt(1)
	v_pk_add_f32 v[78:79], v[78:79], v[84:85]
	ds_bpermute_b32 v82, v168, v80
	ds_bpermute_b32 v85, v168, v79
	ds_bpermute_b32 v84, v168, v78
	v_lshlrev_b32_e32 v110, 16, v110
	s_waitcnt vmcnt(32)
	v_lshlrev_b32_e32 v114, 16, v114
	s_waitcnt lgkmcnt(2)
	v_pk_add_f32 v[80:81], v[80:81], v[82:83]
	s_waitcnt lgkmcnt(0)
	v_pk_add_f32 v[78:79], v[78:79], v[84:85]
	v_pk_fma_f32 v[80:81], v[80:81], s[42:43], v[108:109] op_sel_hi:[1,0,1] neg_lo:[1,0,0] neg_hi:[1,0,0]
	v_pk_fma_f32 v[78:79], v[78:79], s[42:43], v[106:107] op_sel_hi:[1,0,1] neg_lo:[1,0,0] neg_hi:[1,0,0]
	v_pk_mul_f32 v[82:83], v[80:81], v[80:81]
	v_pk_mul_f32 v[84:85], v[78:79], v[78:79]
	s_nop 0
	v_mov_b32_dpp v93, v83 quad_perm:[1,0,3,2] row_mask:0xf bank_mask:0xf
	v_mov_b32_dpp v92, v82 quad_perm:[1,0,3,2] row_mask:0xf bank_mask:0xf
	v_mov_b32_dpp v77, v85 quad_perm:[1,0,3,2] row_mask:0xf bank_mask:0xf
	v_mov_b32_dpp v76, v84 quad_perm:[1,0,3,2] row_mask:0xf bank_mask:0xf
	v_pk_fma_f32 v[82:83], v[80:81], v[80:81], v[92:93]
	v_pk_fma_f32 v[76:77], v[78:79], v[78:79], v[76:77]
	s_nop 0
	v_mov_b32_dpp v91, v83 quad_perm:[2,3,0,1] row_mask:0xf bank_mask:0xf
	v_mov_b32_dpp v90, v82 quad_perm:[2,3,0,1] row_mask:0xf bank_mask:0xf
	v_mov_b32_dpp v75, v77 quad_perm:[2,3,0,1] row_mask:0xf bank_mask:0xf
	v_mov_b32_dpp v74, v76 quad_perm:[2,3,0,1] row_mask:0xf bank_mask:0xf
	v_pk_add_f32 v[82:83], v[82:83], v[90:91]
	v_pk_add_f32 v[74:75], v[76:77], v[74:75]
	s_nop 0
	v_mov_b32_dpp v89, v83 row_half_mirror row_mask:0xf bank_mask:0xf
	v_mov_b32_dpp v88, v82 row_half_mirror row_mask:0xf bank_mask:0xf
	v_mov_b32_dpp v73, v75 row_half_mirror row_mask:0xf bank_mask:0xf
	v_mov_b32_dpp v72, v74 row_half_mirror row_mask:0xf bank_mask:0xf
	v_pk_add_f32 v[76:77], v[82:83], v[88:89]
	v_pk_add_f32 v[72:73], v[74:75], v[72:73]
	s_nop 0
	v_mov_b32_dpp v87, v77 row_mirror row_mask:0xf bank_mask:0xf
	v_mov_b32_dpp v86, v76 row_mirror row_mask:0xf bank_mask:0xf
	v_mov_b32_dpp v71, v73 row_mirror row_mask:0xf bank_mask:0xf
	v_mov_b32_dpp v70, v72 row_mirror row_mask:0xf bank_mask:0xf
	v_pk_add_f32 v[74:75], v[76:77], v[86:87]
	v_pk_add_f32 v[70:71], v[72:73], v[70:71]
	ds_bpermute_b32 v73, v167, v75
	ds_bpermute_b32 v72, v167, v74
	ds_bpermute_b32 v77, v167, v71
	ds_bpermute_b32 v76, v167, v70
	s_waitcnt lgkmcnt(2)
	v_pk_add_f32 v[72:73], v[74:75], v[72:73]
	ds_bpermute_b32 v75, v168, v73
	s_waitcnt lgkmcnt(1)
	v_pk_add_f32 v[70:71], v[70:71], v[76:77]
	ds_bpermute_b32 v74, v168, v72
	ds_bpermute_b32 v77, v168, v71
	ds_bpermute_b32 v76, v168, v70
	s_waitcnt lgkmcnt(2)
	v_pk_add_f32 v[72:73], v[72:73], v[74:75]
	s_nop 0
	v_pk_fma_f32 v[72:73], v[72:73], s[42:43], v[68:69] op_sel_hi:[1,0,0]
	s_waitcnt lgkmcnt(0)
	v_pk_add_f32 v[70:71], v[70:71], v[76:77]
	v_cmp_gt_f32_e64 s[4:5], s74, v73
	v_pk_fma_f32 v[68:69], v[70:71], s[42:43], v[68:69] op_sel_hi:[1,0,0]
	v_mul_f32_e32 v70, 0x4b800000, v73
	v_mul_f32_e32 v71, 0x4b800000, v72
	v_cmp_gt_f32_e32 vcc, s74, v72
	v_mul_f32_e32 v74, 0x4b800000, v69
	v_mul_f32_e32 v75, 0x4b800000, v68
	v_cmp_gt_f32_e64 s[6:7], s74, v68
	v_cndmask_b32_e64 v70, v73, v70, s[4:5]
	v_cmp_gt_f32_e64 s[8:9], s74, v69
	v_cndmask_b32_e32 v71, v72, v71, vcc
	v_cndmask_b32_e64 v68, v68, v75, s[6:7]
	v_cndmask_b32_e64 v69, v69, v74, s[8:9]
	v_rsq_f32_e32 v70, v70
	v_rsq_f32_e32 v71, v71
	v_rsq_f32_e32 v69, v69
	v_rsq_f32_e32 v68, v68
	v_mul_f32_e32 v72, 0x45800000, v70
	v_mul_f32_e32 v73, 0x45800000, v71
	v_mul_f32_e32 v74, 0x45800000, v69
	v_mul_f32_e32 v75, 0x45800000, v68
	v_cndmask_b32_e64 v70, v70, v72, s[4:5]
	v_cndmask_b32_e32 v71, v71, v73, vcc
	v_cndmask_b32_e64 v69, v69, v74, s[8:9]
	v_cndmask_b32_e64 v68, v68, v75, s[6:7]
	v_mul_f32_e32 v70, v81, v70
	v_mul_f32_e32 v71, v80, v71
	v_mul_f32_e32 v69, v79, v69
	v_mul_f32_e32 v68, v78, v68
	s_waitcnt vmcnt(25)
	v_fmac_f32_e32 v125, v121, v70
	s_waitcnt vmcnt(24)
	v_fmac_f32_e32 v126, v122, v71
	v_fmac_f32_e32 v123, v115, v69
	v_fmac_f32_e32 v124, v120, v68
	v_add_f32_e32 v68, v125, v116
	v_add_f32_e32 v69, v126, v113
	v_add_f32_e32 v64, v123, v64
	v_add_f32_e32 v70, v124, v111
	v_mul_f32_e32 v68, v68, v112
	v_mul_f32_e32 v69, v69, v114
	v_mul_f32_e32 v64, v64, v127
	v_mul_f32_e32 v70, v70, v110
	v_bfe_u32 v71, v68, 16, 1
	v_bfe_u32 v72, v69, 16, 1
	v_bfe_u32 v73, v64, 16, 1
	v_bfe_u32 v74, v70, 16, 1
	v_add3_u32 v68, v68, v71, s78
	v_add3_u32 v69, v69, v72, s78
	v_add3_u32 v64, v64, v73, s78
	v_add3_u32 v70, v70, v74, s78
	global_store_short_d16_hi v[100:101], v68, off offset:256
	global_store_short_d16_hi v[100:101], v69, off offset:384
	global_store_short_d16_hi v[104:105], v64, off offset:2048
	global_store_short_d16_hi v[100:101], v70, off offset:128
	s_branch .Lrwf_loop
.Lrwf_tail1:
	s_waitcnt vmcnt(0)
	v_mov_b32_e32 v35, v1
	v_mov_b32_e32 v34, v1
	v_mov_b32_e32 v15, v1
	v_mov_b32_e32 v14, v1
	v_mov_b32_e32 v39, v1
	v_mov_b32_e32 v38, v1
	v_mov_b32_e32 v21, v1
	v_mov_b32_e32 v20, v1
	v_mov_b32_e32 v33, v1
	v_mov_b32_e32 v32, v1
	v_mov_b32_e32 v19, v1
	v_mov_b32_e32 v18, v1
	v_mov_b32_e32 v31, v1
	v_mov_b32_e32 v30, v1
	v_mov_b32_e32 v17, v1
	v_mov_b32_e32 v16, v1
	v_mov_b32_e32 v29, v1
	v_mov_b32_e32 v28, v1
	v_mov_b32_e32 v13, v1
	v_mov_b32_e32 v12, v1
	v_mov_b32_e32 v27, v1
	v_mov_b32_e32 v26, v1
	v_mov_b32_e32 v11, v1
	v_mov_b32_e32 v10, v1
	v_mov_b32_e32 v25, v1
	v_mov_b32_e32 v24, v1
	v_mov_b32_e32 v9, v1
	v_mov_b32_e32 v8, v1
	v_mov_b32_e32 v23, v1
	v_mov_b32_e32 v22, v1
	v_mov_b32_e32 v7, v1
	v_mov_b32_e32 v6, v1
	s_waitcnt vmcnt(19)
	v_lshlrev_b32_e32 v0, 16, v0
	s_waitcnt vmcnt(18)
	v_lshlrev_b32_e32 v63, 16, v42
	s_waitcnt vmcnt(17)
	v_lshlrev_b32_e32 v42, 16, v43
	s_waitcnt vmcnt(16)
	v_lshlrev_b32_e32 v45, 16, v52
	s_waitcnt vmcnt(15)
	v_lshlrev_b32_e32 v44, 16, v53
	v_mov_b32_dpp v14, v42 quad_perm:[1,0,3,2] row_mask:0xf bank_mask:0xf
	v_mov_b32_dpp v35, v45 quad_perm:[1,0,3,2] row_mask:0xf bank_mask:0xf
	s_waitcnt vmcnt(12)
	v_lshlrev_b32_e32 v43, 16, v47
	v_mov_b32_dpp v34, v44 quad_perm:[1,0,3,2] row_mask:0xf bank_mask:0xf
	v_pk_add_f32 v[34:35], v[44:45], v[34:35]
	v_mov_b32_dpp v15, v43 quad_perm:[1,0,3,2] row_mask:0xf bank_mask:0xf
	v_pk_add_f32 v[14:15], v[42:43], v[14:15]
	v_mov_b32_dpp v39, v35 quad_perm:[2,3,0,1] row_mask:0xf bank_mask:0xf
	v_mov_b32_dpp v38, v34 quad_perm:[2,3,0,1] row_mask:0xf bank_mask:0xf
	v_mov_b32_dpp v21, v15 quad_perm:[2,3,0,1] row_mask:0xf bank_mask:0xf
	v_mov_b32_dpp v20, v14 quad_perm:[2,3,0,1] row_mask:0xf bank_mask:0xf
	v_pk_add_f32 v[34:35], v[34:35], v[38:39]
	v_pk_add_f32 v[14:15], v[14:15], v[20:21]
	s_waitcnt vmcnt(11)
	v_lshlrev_b32_e32 v52, 16, v55
	v_mov_b32_dpp v33, v35 row_half_mirror row_mask:0xf bank_mask:0xf
	v_mov_b32_dpp v32, v34 row_half_mirror row_mask:0xf bank_mask:0xf
	v_mov_b32_dpp v19, v15 row_half_mirror row_mask:0xf bank_mask:0xf
	v_mov_b32_dpp v18, v14 row_half_mirror row_mask:0xf bank_mask:0xf
	v_pk_add_f32 v[20:21], v[34:35], v[32:33]
	v_pk_add_f32 v[14:15], v[14:15], v[18:19]
	v_lshlrev_b32_e32 v47, 16, v54
	v_mov_b32_dpp v31, v21 row_mirror row_mask:0xf bank_mask:0xf
	v_mov_b32_dpp v30, v20 row_mirror row_mask:0xf bank_mask:0xf
	v_mov_b32_dpp v17, v15 row_mirror row_mask:0xf bank_mask:0xf
	v_mov_b32_dpp v16, v14 row_mirror row_mask:0xf bank_mask:0xf
	v_pk_add_f32 v[18:19], v[20:21], v[30:31]
	v_pk_add_f32 v[14:15], v[14:15], v[16:17]
	ds_bpermute_b32 v17, v167, v19
	ds_bpermute_b32 v16, v167, v18
	ds_bpermute_b32 v21, v167, v15
	ds_bpermute_b32 v20, v167, v14
	s_waitcnt vmcnt(10)
	v_lshlrev_b32_e32 v48, 16, v48
	s_waitcnt vmcnt(9)
	v_lshlrev_b32_e32 v49, 16, v49
	s_waitcnt lgkmcnt(2)
	v_pk_add_f32 v[16:17], v[18:19], v[16:17]
	ds_bpermute_b32 v19, v168, v17
	s_waitcnt lgkmcnt(1)
	v_pk_add_f32 v[14:15], v[14:15], v[20:21]
	ds_bpermute_b32 v18, v168, v16
	ds_bpermute_b32 v21, v168, v15
	ds_bpermute_b32 v20, v168, v14
	v_lshlrev_b32_e32 v46, 16, v46
	s_waitcnt vmcnt(8)
	v_lshlrev_b32_e32 v50, 16, v50
	s_waitcnt lgkmcnt(2)
	v_pk_add_f32 v[16:17], v[16:17], v[18:19]
	s_waitcnt lgkmcnt(0)
	v_pk_add_f32 v[14:15], v[14:15], v[20:21]
	v_pk_fma_f32 v[16:17], v[16:17], s[42:43], v[44:45] op_sel_hi:[1,0,1] neg_lo:[1,0,0] neg_hi:[1,0,0]
	v_pk_fma_f32 v[14:15], v[14:15], s[42:43], v[42:43] op_sel_hi:[1,0,1] neg_lo:[1,0,0] neg_hi:[1,0,0]
	v_pk_mul_f32 v[18:19], v[16:17], v[16:17]
	v_pk_mul_f32 v[20:21], v[14:15], v[14:15]
	s_nop 0
	v_mov_b32_dpp v29, v19 quad_perm:[1,0,3,2] row_mask:0xf bank_mask:0xf
	v_mov_b32_dpp v28, v18 quad_perm:[1,0,3,2] row_mask:0xf bank_mask:0xf
	v_mov_b32_dpp v13, v21 quad_perm:[1,0,3,2] row_mask:0xf bank_mask:0xf
	v_mov_b32_dpp v12, v20 quad_perm:[1,0,3,2] row_mask:0xf bank_mask:0xf
	v_pk_fma_f32 v[18:19], v[16:17], v[16:17], v[28:29]
	v_pk_fma_f32 v[12:13], v[14:15], v[14:15], v[12:13]
	s_nop 0
	v_mov_b32_dpp v27, v19 quad_perm:[2,3,0,1] row_mask:0xf bank_mask:0xf
	v_mov_b32_dpp v26, v18 quad_perm:[2,3,0,1] row_mask:0xf bank_mask:0xf
	v_mov_b32_dpp v11, v13 quad_perm:[2,3,0,1] row_mask:0xf bank_mask:0xf
	v_mov_b32_dpp v10, v12 quad_perm:[2,3,0,1] row_mask:0xf bank_mask:0xf
	v_pk_add_f32 v[18:19], v[18:19], v[26:27]
	v_pk_add_f32 v[10:11], v[12:13], v[10:11]
	s_nop 0
	v_mov_b32_dpp v25, v19 row_half_mirror row_mask:0xf bank_mask:0xf
	v_mov_b32_dpp v24, v18 row_half_mirror row_mask:0xf bank_mask:0xf
	v_mov_b32_dpp v9, v11 row_half_mirror row_mask:0xf bank_mask:0xf
	v_mov_b32_dpp v8, v10 row_half_mirror row_mask:0xf bank_mask:0xf
	v_pk_add_f32 v[12:13], v[18:19], v[24:25]
	v_pk_add_f32 v[8:9], v[10:11], v[8:9]
	s_nop 0
	v_mov_b32_dpp v23, v13 row_mirror row_mask:0xf bank_mask:0xf
	v_mov_b32_dpp v22, v12 row_mirror row_mask:0xf bank_mask:0xf
	v_mov_b32_dpp v7, v9 row_mirror row_mask:0xf bank_mask:0xf
	v_mov_b32_dpp v6, v8 row_mirror row_mask:0xf bank_mask:0xf
	v_pk_add_f32 v[10:11], v[12:13], v[22:23]
	v_pk_add_f32 v[6:7], v[8:9], v[6:7]
	ds_bpermute_b32 v9, v167, v11
	ds_bpermute_b32 v8, v167, v10
	ds_bpermute_b32 v13, v167, v7
	ds_bpermute_b32 v12, v167, v6
	s_waitcnt lgkmcnt(2)
	v_pk_add_f32 v[8:9], v[10:11], v[8:9]
	ds_bpermute_b32 v11, v168, v9
	s_waitcnt lgkmcnt(1)
	v_pk_add_f32 v[6:7], v[6:7], v[12:13]
	ds_bpermute_b32 v10, v168, v8
	ds_bpermute_b32 v13, v168, v7
	ds_bpermute_b32 v12, v168, v6
	s_waitcnt lgkmcnt(2)
	v_pk_add_f32 v[8:9], v[8:9], v[10:11]
	s_nop 0
	v_pk_fma_f32 v[8:9], v[8:9], s[42:43], v[4:5] op_sel_hi:[1,0,0]
	s_waitcnt lgkmcnt(0)
	v_pk_add_f32 v[6:7], v[6:7], v[12:13]
	v_cmp_gt_f32_e64 s[4:5], s74, v9
	v_pk_fma_f32 v[4:5], v[6:7], s[42:43], v[4:5] op_sel_hi:[1,0,0]
	v_mul_f32_e32 v6, 0x4b800000, v9
	v_mul_f32_e32 v7, 0x4b800000, v8
	v_cmp_gt_f32_e32 vcc, s74, v8
	v_mul_f32_e32 v10, 0x4b800000, v5
	v_mul_f32_e32 v11, 0x4b800000, v4
	v_cmp_gt_f32_e64 s[6:7], s74, v4
	v_cndmask_b32_e64 v6, v9, v6, s[4:5]
	v_cmp_gt_f32_e64 s[8:9], s74, v5
	v_cndmask_b32_e32 v7, v8, v7, vcc
	v_cndmask_b32_e64 v4, v4, v11, s[6:7]
	v_cndmask_b32_e64 v5, v5, v10, s[8:9]
	v_rsq_f32_e32 v6, v6
	v_rsq_f32_e32 v7, v7
	v_rsq_f32_e32 v5, v5
	v_rsq_f32_e32 v4, v4
	v_mul_f32_e32 v8, 0x45800000, v6
	v_mul_f32_e32 v9, 0x45800000, v7
	v_mul_f32_e32 v10, 0x45800000, v5
	v_mul_f32_e32 v11, 0x45800000, v4
	v_cndmask_b32_e64 v6, v6, v8, s[4:5]
	v_cndmask_b32_e32 v7, v7, v9, vcc
	v_cndmask_b32_e64 v5, v5, v10, s[8:9]
	v_cndmask_b32_e64 v4, v4, v11, s[6:7]
	v_mul_f32_e32 v6, v17, v6
	v_mul_f32_e32 v7, v16, v7
	v_mul_f32_e32 v5, v15, v5
	v_mul_f32_e32 v4, v14, v4
	s_waitcnt vmcnt(1)
	v_fmac_f32_e32 v61, v57, v6
	s_waitcnt vmcnt(0)
	v_fmac_f32_e32 v62, v58, v7
	v_fmac_f32_e32 v59, v51, v5
	v_fmac_f32_e32 v60, v56, v4
	v_add_f32_e32 v4, v61, v52
	v_add_f32_e32 v5, v62, v49
	v_add_f32_e32 v0, v59, v0
	v_add_f32_e32 v6, v60, v47
	v_mul_f32_e32 v4, v4, v48
	v_mul_f32_e32 v5, v5, v50
	v_mul_f32_e32 v0, v0, v63
	v_mul_f32_e32 v6, v6, v46
	v_bfe_u32 v7, v4, 16, 1
	v_bfe_u32 v8, v5, 16, 1
	v_bfe_u32 v9, v0, 16, 1
	v_bfe_u32 v10, v6, 16, 1
	v_add3_u32 v4, v4, v7, s78
	v_add3_u32 v5, v5, v8, s78
	v_add3_u32 v0, v0, v9, s78
	v_add3_u32 v6, v6, v10, s78
	global_store_short_d16_hi v[36:37], v4, off offset:256
	global_store_short_d16_hi v[36:37], v5, off offset:384
	global_store_short_d16_hi v[40:41], v0, off offset:2048
	global_store_short_d16_hi v[36:37], v6, off offset:128
	s_branch .LBB0_167
.Lrwf_tail2:
	s_waitcnt vmcnt(0)
	v_mov_b32_e32 v99, v1
	v_mov_b32_e32 v98, v1
	v_mov_b32_e32 v79, v1
	v_mov_b32_e32 v78, v1
	v_mov_b32_e32 v103, v1
	v_mov_b32_e32 v102, v1
	v_mov_b32_e32 v85, v1
	v_mov_b32_e32 v84, v1
	v_mov_b32_e32 v97, v1
	v_mov_b32_e32 v96, v1
	v_mov_b32_e32 v83, v1
	v_mov_b32_e32 v82, v1
	v_mov_b32_e32 v95, v1
	v_mov_b32_e32 v94, v1
	v_mov_b32_e32 v81, v1
	v_mov_b32_e32 v80, v1
	v_mov_b32_e32 v93, v1
	v_mov_b32_e32 v92, v1
	v_mov_b32_e32 v77, v1
	v_mov_b32_e32 v76, v1
	v_mov_b32_e32 v91, v1
	v_mov_b32_e32 v90, v1
	v_mov_b32_e32 v75, v1
	v_mov_b32_e32 v74, v1
	v_mov_b32_e32 v89, v1
	v_mov_b32_e32 v88, v1
	v_mov_b32_e32 v73, v1
	v_mov_b32_e32 v72, v1
	v_mov_b32_e32 v87, v1
	v_mov_b32_e32 v86, v1
	v_mov_b32_e32 v71, v1
	v_mov_b32_e32 v70, v1
	s_waitcnt vmcnt(19)
	v_lshlrev_b32_e32 v64, 16, v64
	s_waitcnt vmcnt(18)
	v_lshlrev_b32_e32 v127, 16, v106
	s_waitcnt vmcnt(17)
	v_lshlrev_b32_e32 v106, 16, v107
	s_waitcnt vmcnt(16)
	v_lshlrev_b32_e32 v109, 16, v116
	s_waitcnt vmcnt(15)
	v_lshlrev_b32_e32 v108, 16, v117
	v_mov_b32_dpp v78, v106 quad_perm:[1,0,3,2] row_mask:0xf bank_mask:0xf
	v_mov_b32_dpp v99, v109 quad_perm:[1,0,3,2] row_mask:0xf bank_mask:0xf
	s_waitcnt vmcnt(12)
	v_lshlrev_b32_e32 v107, 16, v111
	v_mov_b32_dpp v98, v108 quad_perm:[1,0,3,2] row_mask:0xf bank_mask:0xf
	v_pk_add_f32 v[98:99], v[108:109], v[98:99]
	v_mov_b32_dpp v79, v107 quad_perm:[1,0,3,2] row_mask:0xf bank_mask:0xf
	v_pk_add_f32 v[78:79], v[106:107], v[78:79]
	v_mov_b32_dpp v103, v99 quad_perm:[2,3,0,1] row_mask:0xf bank_mask:0xf
	v_mov_b32_dpp v102, v98 quad_perm:[2,3,0,1] row_mask:0xf bank_mask:0xf
	v_mov_b32_dpp v85, v79 quad_perm:[2,3,0,1] row_mask:0xf bank_mask:0xf
	v_mov_b32_dpp v84, v78 quad_perm:[2,3,0,1] row_mask:0xf bank_mask:0xf
	v_pk_add_f32 v[98:99], v[98:99], v[102:103]
	v_pk_add_f32 v[78:79], v[78:79], v[84:85]
	s_waitcnt vmcnt(11)
	v_lshlrev_b32_e32 v116, 16, v119
	v_mov_b32_dpp v97, v99 row_half_mirror row_mask:0xf bank_mask:0xf
	v_mov_b32_dpp v96, v98 row_half_mirror row_mask:0xf bank_mask:0xf
	v_mov_b32_dpp v83, v79 row_half_mirror row_mask:0xf bank_mask:0xf
	v_mov_b32_dpp v82, v78 row_half_mirror row_mask:0xf bank_mask:0xf
	v_pk_add_f32 v[84:85], v[98:99], v[96:97]
	v_pk_add_f32 v[78:79], v[78:79], v[82:83]
	v_lshlrev_b32_e32 v111, 16, v118
	v_mov_b32_dpp v95, v85 row_mirror row_mask:0xf bank_mask:0xf
	v_mov_b32_dpp v94, v84 row_mirror row_mask:0xf bank_mask:0xf
	v_mov_b32_dpp v81, v79 row_mirror row_mask:0xf bank_mask:0xf
	v_mov_b32_dpp v80, v78 row_mirror row_mask:0xf bank_mask:0xf
	v_pk_add_f32 v[82:83], v[84:85], v[94:95]
	v_pk_add_f32 v[78:79], v[78:79], v[80:81]
	ds_bpermute_b32 v81, v167, v83
	ds_bpermute_b32 v80, v167, v82
	ds_bpermute_b32 v85, v167, v79
	ds_bpermute_b32 v84, v167, v78
	s_waitcnt vmcnt(10)
	v_lshlrev_b32_e32 v112, 16, v112
	s_waitcnt vmcnt(9)
	v_lshlrev_b32_e32 v113, 16, v113
	s_waitcnt lgkmcnt(2)
	v_pk_add_f32 v[80:81], v[82:83], v[80:81]
	ds_bpermute_b32 v83, v168, v81
	s_waitcnt lgkmcnt(1)
	v_pk_add_f32 v[78:79], v[78:79], v[84:85]
	ds_bpermute_b32 v82, v168, v80
	ds_bpermute_b32 v85, v168, v79
	ds_bpermute_b32 v84, v168, v78
	v_lshlrev_b32_e32 v110, 16, v110
	s_waitcnt vmcnt(8)
	v_lshlrev_b32_e32 v114, 16, v114
	s_waitcnt lgkmcnt(2)
	v_pk_add_f32 v[80:81], v[80:81], v[82:83]
	s_waitcnt lgkmcnt(0)
	v_pk_add_f32 v[78:79], v[78:79], v[84:85]
	v_pk_fma_f32 v[80:81], v[80:81], s[42:43], v[108:109] op_sel_hi:[1,0,1] neg_lo:[1,0,0] neg_hi:[1,0,0]
	v_pk_fma_f32 v[78:79], v[78:79], s[42:43], v[106:107] op_sel_hi:[1,0,1] neg_lo:[1,0,0] neg_hi:[1,0,0]
	v_pk_mul_f32 v[82:83], v[80:81], v[80:81]
	v_pk_mul_f32 v[84:85], v[78:79], v[78:79]
	s_nop 0
	v_mov_b32_dpp v93, v83 quad_perm:[1,0,3,2] row_mask:0xf bank_mask:0xf
	v_mov_b32_dpp v92, v82 quad_perm:[1,0,3,2] row_mask:0xf bank_mask:0xf
	v_mov_b32_dpp v77, v85 quad_perm:[1,0,3,2] row_mask:0xf bank_mask:0xf
	v_mov_b32_dpp v76, v84 quad_perm:[1,0,3,2] row_mask:0xf bank_mask:0xf
	v_pk_fma_f32 v[82:83], v[80:81], v[80:81], v[92:93]
	v_pk_fma_f32 v[76:77], v[78:79], v[78:79], v[76:77]
	s_nop 0
	v_mov_b32_dpp v91, v83 quad_perm:[2,3,0,1] row_mask:0xf bank_mask:0xf
	v_mov_b32_dpp v90, v82 quad_perm:[2,3,0,1] row_mask:0xf bank_mask:0xf
	v_mov_b32_dpp v75, v77 quad_perm:[2,3,0,1] row_mask:0xf bank_mask:0xf
	v_mov_b32_dpp v74, v76 quad_perm:[2,3,0,1] row_mask:0xf bank_mask:0xf
	v_pk_add_f32 v[82:83], v[82:83], v[90:91]
	v_pk_add_f32 v[74:75], v[76:77], v[74:75]
	s_nop 0
	v_mov_b32_dpp v89, v83 row_half_mirror row_mask:0xf bank_mask:0xf
	v_mov_b32_dpp v88, v82 row_half_mirror row_mask:0xf bank_mask:0xf
	v_mov_b32_dpp v73, v75 row_half_mirror row_mask:0xf bank_mask:0xf
	v_mov_b32_dpp v72, v74 row_half_mirror row_mask:0xf bank_mask:0xf
	v_pk_add_f32 v[76:77], v[82:83], v[88:89]
	v_pk_add_f32 v[72:73], v[74:75], v[72:73]
	s_nop 0
	v_mov_b32_dpp v87, v77 row_mirror row_mask:0xf bank_mask:0xf
	v_mov_b32_dpp v86, v76 row_mirror row_mask:0xf bank_mask:0xf
	v_mov_b32_dpp v71, v73 row_mirror row_mask:0xf bank_mask:0xf
	v_mov_b32_dpp v70, v72 row_mirror row_mask:0xf bank_mask:0xf
	v_pk_add_f32 v[74:75], v[76:77], v[86:87]
	v_pk_add_f32 v[70:71], v[72:73], v[70:71]
	ds_bpermute_b32 v73, v167, v75
	ds_bpermute_b32 v72, v167, v74
	ds_bpermute_b32 v77, v167, v71
	ds_bpermute_b32 v76, v167, v70
	s_waitcnt lgkmcnt(2)
	v_pk_add_f32 v[72:73], v[74:75], v[72:73]
	ds_bpermute_b32 v75, v168, v73
	s_waitcnt lgkmcnt(1)
	v_pk_add_f32 v[70:71], v[70:71], v[76:77]
	ds_bpermute_b32 v74, v168, v72
	ds_bpermute_b32 v77, v168, v71
	ds_bpermute_b32 v76, v168, v70
	s_waitcnt lgkmcnt(2)
	v_pk_add_f32 v[72:73], v[72:73], v[74:75]
	s_nop 0
	v_pk_fma_f32 v[72:73], v[72:73], s[42:43], v[68:69] op_sel_hi:[1,0,0]
	s_waitcnt lgkmcnt(0)
	v_pk_add_f32 v[70:71], v[70:71], v[76:77]
	v_cmp_gt_f32_e64 s[4:5], s74, v73
	v_pk_fma_f32 v[68:69], v[70:71], s[42:43], v[68:69] op_sel_hi:[1,0,0]
	v_mul_f32_e32 v70, 0x4b800000, v73
	v_mul_f32_e32 v71, 0x4b800000, v72
	v_cmp_gt_f32_e32 vcc, s74, v72
	v_mul_f32_e32 v74, 0x4b800000, v69
	v_mul_f32_e32 v75, 0x4b800000, v68
	v_cmp_gt_f32_e64 s[6:7], s74, v68
	v_cndmask_b32_e64 v70, v73, v70, s[4:5]
	v_cmp_gt_f32_e64 s[8:9], s74, v69
	v_cndmask_b32_e32 v71, v72, v71, vcc
	v_cndmask_b32_e64 v68, v68, v75, s[6:7]
	v_cndmask_b32_e64 v69, v69, v74, s[8:9]
	v_rsq_f32_e32 v70, v70
	v_rsq_f32_e32 v71, v71
	v_rsq_f32_e32 v69, v69
	v_rsq_f32_e32 v68, v68
	v_mul_f32_e32 v72, 0x45800000, v70
	v_mul_f32_e32 v73, 0x45800000, v71
	v_mul_f32_e32 v74, 0x45800000, v69
	v_mul_f32_e32 v75, 0x45800000, v68
	v_cndmask_b32_e64 v70, v70, v72, s[4:5]
	v_cndmask_b32_e32 v71, v71, v73, vcc
	v_cndmask_b32_e64 v69, v69, v74, s[8:9]
	v_cndmask_b32_e64 v68, v68, v75, s[6:7]
	v_mul_f32_e32 v70, v81, v70
	v_mul_f32_e32 v71, v80, v71
	v_mul_f32_e32 v69, v79, v69
	v_mul_f32_e32 v68, v78, v68
	s_waitcnt vmcnt(1)
	v_fmac_f32_e32 v125, v121, v70
	s_waitcnt vmcnt(0)
	v_fmac_f32_e32 v126, v122, v71
	v_fmac_f32_e32 v123, v115, v69
	v_fmac_f32_e32 v124, v120, v68
	v_add_f32_e32 v68, v125, v116
	v_add_f32_e32 v69, v126, v113
	v_add_f32_e32 v64, v123, v64
	v_add_f32_e32 v70, v124, v111
	v_mul_f32_e32 v68, v68, v112
	v_mul_f32_e32 v69, v69, v114
	v_mul_f32_e32 v64, v64, v127
	v_mul_f32_e32 v70, v70, v110
	v_bfe_u32 v71, v68, 16, 1
	v_bfe_u32 v72, v69, 16, 1
	v_bfe_u32 v73, v64, 16, 1
	v_bfe_u32 v74, v70, 16, 1
	v_add3_u32 v68, v68, v71, s78
	v_add3_u32 v69, v69, v72, s78
	v_add3_u32 v64, v64, v73, s78
	v_add3_u32 v70, v70, v74, s78
	global_store_short_d16_hi v[100:101], v68, off offset:256
	global_store_short_d16_hi v[100:101], v69, off offset:384
	global_store_short_d16_hi v[104:105], v64, off offset:2048
	global_store_short_d16_hi v[100:101], v70, off offset:128
